# prep_rs before G1/G3/G7: all four rounds' loads issued first (own registers), one wait, then the reductions
# speedup vs baseline: 1.0198x; 1.0051x over previous
.LBB0_135:
	s_ashr_i32 s1, s2, 31
	s_lshr_b32 s0, s1, 29
	s_add_i32 s0, s2, s0
	s_ashr_i32 s3, s0, 3
	s_and_b32 s0, s0, -8
	s_ashr_i32 s50, s94, 31
	s_sub_i32 s0, s2, s0
	s_cmp_lt_i32 s0, 0
	v_writelane_b32 v240, s3, 28
	s_cselect_b64 s[4:5], -1, 0
	v_writelane_b32 v240, s4, 29
	s_lshl_b32 s3, s0, 7
	s_waitcnt lgkmcnt(0)
	v_mov_b64_e32 v[0:1], 0x400
	v_writelane_b32 v240, s5, 30
	v_writelane_b32 v240, s3, 31
	v_writelane_b32 v240, s0, 32
	s_mulk_i32 s0, 0x81
	s_add_u32 s4, s94, s2
	v_writelane_b32 v240, s0, 33
	s_addc_u32 s5, s50, s1
	v_writelane_b32 v240, s1, 34
	v_cmp_lt_i64_e64 s[0:1], s[4:5], v[0:1]
	s_barrier
	s_add_u32 s6, s92, 0x513600
	s_addc_u32 s7, s93, 0
	v_mov_b32_e32 v4, 0
	global_load_dword v5, v4, s[6:7] offset:0 sc1
	global_load_dword v6, v4, s[6:7] offset:256 sc1
	global_load_dword v7, v4, s[6:7] offset:512 sc1
	global_load_dword v8, v4, s[6:7] offset:768 sc1
	global_load_dword v9, v4, s[6:7] offset:1024 sc1
	global_load_dword v10, v4, s[6:7] offset:1280 sc1
	global_load_dword v11, v4, s[6:7] offset:1536 sc1
	global_load_dword v12, v4, s[6:7] offset:1792 sc1
	s_waitcnt vmcnt(0)
	v_mov_b32_e32 v13, -1
	v_mov_b32_e32 v14, 0
	v_min_u32_e32 v13, v13, v5
	v_add_u32_e32 v15, -1, v5
	v_and_b32_e32 v15, v15, v5
	v_or_b32_e32 v14, v14, v15
	v_min_u32_e32 v13, v13, v6
	v_add_u32_e32 v15, -1, v6
	v_and_b32_e32 v15, v15, v6
	v_or_b32_e32 v14, v14, v15
	v_min_u32_e32 v13, v13, v7
	v_add_u32_e32 v15, -1, v7
	v_and_b32_e32 v15, v15, v7
	v_or_b32_e32 v14, v14, v15
	v_min_u32_e32 v13, v13, v8
	v_add_u32_e32 v15, -1, v8
	v_and_b32_e32 v15, v15, v8
	v_or_b32_e32 v14, v14, v15
	v_min_u32_e32 v13, v13, v9
	v_add_u32_e32 v15, -1, v9
	v_and_b32_e32 v15, v15, v9
	v_or_b32_e32 v14, v14, v15
	v_min_u32_e32 v13, v13, v10
	v_add_u32_e32 v15, -1, v10
	v_and_b32_e32 v15, v15, v10
	v_or_b32_e32 v14, v14, v15
	v_min_u32_e32 v13, v13, v11
	v_add_u32_e32 v15, -1, v11
	v_and_b32_e32 v15, v15, v11
	v_or_b32_e32 v14, v14, v15
	v_min_u32_e32 v13, v13, v12
	v_add_u32_e32 v15, -1, v12
	v_and_b32_e32 v15, v15, v12
	v_or_b32_e32 v14, v14, v15
	v_cmp_ne_u32_e32 vcc, 0, v13
	s_nop 1
	v_cndmask_b32_e64 v13, 0, 1, vcc
	v_cmp_eq_u32_e32 vcc, 0, v14
	s_nop 1
	v_cndmask_b32_e32 v13, 0, v13, vcc
	v_mov_b32_e32 v14, 0x23ff8
	ds_write_b32 v14, v13
	v_mov_b32_e32 v15, 0
	ds_write_b32 v14, v15 offset:4
	s_waitcnt lgkmcnt(0)
	s_nop 0
	v_writelane_b32 v240, s0, 35
	s_nop 1
	v_writelane_b32 v240, s1, 36
	s_ashr_i32 s0, s4, 31
	s_lshr_b32 s0, s0, 29
	s_add_i32 s0, s4, s0
	s_ashr_i32 s1, s0, 3
	s_and_b32 s0, s0, -8
	s_sub_i32 s3, s4, s0
	s_cmp_lt_i32 s3, 0
	v_writelane_b32 v240, s1, 37
	s_cselect_b64 s[0:1], -1, 0
	v_writelane_b32 v240, s0, 38
	s_nop 1
	v_writelane_b32 v240, s1, 39
	s_lshl_b32 s0, s3, 7
	v_writelane_b32 v240, s0, 40
	v_writelane_b32 v240, s3, 41
	s_mul_i32 s0, s3, 0x81
	v_writelane_b32 v240, s0, 42
	s_add_u32 s6, s4, s94
	v_writelane_b32 v240, s4, 43
	s_addc_u32 s7, s5, s50
	v_cmp_lt_i64_e64 s[0:1], s[6:7], v[0:1]
	v_writelane_b32 v240, s5, 44
	s_nop 0
	v_writelane_b32 v240, s0, 45
	s_nop 1
	v_writelane_b32 v240, s1, 46
	s_ashr_i32 s0, s6, 31
	s_lshr_b32 s0, s0, 29
	s_add_i32 s0, s6, s0
	s_ashr_i32 s1, s0, 3
	s_and_b32 s0, s0, -8
	s_sub_i32 s3, s6, s0
	s_cmp_lt_i32 s3, 0
	v_writelane_b32 v240, s1, 47
	s_cselect_b64 s[0:1], -1, 0
	v_writelane_b32 v240, s0, 48
	s_nop 1
	v_writelane_b32 v240, s1, 49
	s_lshl_b32 s0, s3, 7
	v_writelane_b32 v240, s0, 50
	v_writelane_b32 v240, s3, 51
	s_mul_i32 s0, s3, 0x81
	v_writelane_b32 v240, s0, 52
	s_add_u32 s4, s6, s94
	v_writelane_b32 v240, s6, 53
	s_addc_u32 s5, s7, s50
	v_cmp_lt_i64_e64 s[0:1], s[4:5], v[0:1]
	v_writelane_b32 v240, s7, 54
	v_mbcnt_lo_u32_b32 v0, -1, 0
	v_mbcnt_hi_u32_b32 v0, -1, v0
	s_nop 0
	v_writelane_b32 v240, s0, 55
	s_nop 1
	v_writelane_b32 v240, s1, 56
	s_ashr_i32 s0, s4, 31
	s_lshr_b32 s0, s0, 29
	s_add_i32 s0, s4, s0
	s_ashr_i32 s1, s0, 3
	v_writelane_b32 v240, s1, 57
	s_and_b32 s0, s0, -8
	v_writelane_b32 v240, s4, 58
	s_sub_i32 s3, s4, s0
	s_cmp_lt_i32 s3, 0
	v_writelane_b32 v240, s5, 59
	s_cselect_b64 s[0:1], -1, 0
	v_writelane_b32 v240, s0, 60
	s_nop 1
	v_writelane_b32 v240, s1, 61
	s_lshl_b32 s0, s3, 7
	v_writelane_b32 v240, s0, 62
	s_mul_i32 s0, s3, 0x81
	v_writelane_b32 v241, s0, 0
	v_readlane_b32 s0, v242, 8
	s_cmpk_lt_i32 s2, 0x400
	v_writelane_b32 v240, s3, 63
	v_add_u32_e32 v1, s0, v0
	s_movk_i32 s0, 0x100
	v_cmp_gt_i32_e32 vcc, s0, v1
	s_cselect_b64 s[0:1], -1, 0
	v_cndmask_b32_e64 v0, 0, 1, s[0:1]
	v_cmp_ne_u32_e64 s[52:53], 1, v0
	s_and_saveexec_b64 s[0:1], vcc
	s_cbranch_execz .LBB0_144
	s_waitcnt vmcnt(0)
	s_add_i32 s3, 0, 0x20000
	s_and_b64 vcc, exec, s[52:53]
	v_lshl_add_u32 v0, v1, 2, s3
	s_cbranch_vccnz .Lprs0_p1
	v_readlane_b32 s4, v240, 29
	v_readlane_b32 s5, v240, 30
	s_and_b64 s[4:5], s[4:5], exec
	v_readlane_b32 s3, v240, 31
	v_readlane_b32 s4, v240, 33
	s_cselect_b32 s3, s4, s3
	v_readlane_b32 s4, v240, 28
	s_add_i32 s3, s3, s4
	s_ashr_i32 s4, s3, 31
	s_lshr_b32 s4, s4, 25
	s_add_i32 s4, s3, s4
	s_and_b32 s5, s4, 0xff80
	s_sub_i32 s3, s3, s5
	s_bfe_i32 s5, s3, 0x80000
	s_bfe_u32 s5, s5, 0x3000c
	s_add_i32 s5, s3, s5
	s_and_b32 s5, s5, 0xf8
	s_sub_i32 s3, s3, s5
	s_sext_i32_i8 s3, s3
	s_lshl_b32 s4, s4, 4
	s_and_b32 s4, s4, 0xfffff800
	s_lshl_b32 s3, s3, 8
	s_add_i32 s3, s3, s4
	v_add_u32_e32 v2, s3, v1
	v_ashrrev_i32_e32 v3, 31, v2
	v_lshlrev_b64 v[2:3], 6, v[2:3]
	v_lshl_add_u64 v[14:15], s[92:93], 0, v[2:3]
	global_load_dwordx4 v[2:5], v[14:15], off
	global_load_dwordx4 v[6:9], v[14:15], off offset:16
	global_load_dwordx4 v[10:13], v[14:15], off offset:32
	s_nop 0
	global_load_dwordx4 v[14:17], v[14:15], off offset:48
.Lprs0_p1:
	v_readlane_b32 s4, v240, 35
	v_readlane_b32 s5, v240, 36
	s_andn2_b64 vcc, exec, s[4:5]
	s_cbranch_vccnz .Lprs0_p2
	v_readlane_b32 s4, v240, 38
	v_readlane_b32 s5, v240, 39
	s_and_b64 s[4:5], s[4:5], exec
	v_readlane_b32 s4, v240, 41
	v_readlane_b32 s3, v240, 40
	s_mulk_i32 s4, 0x81
	s_cselect_b32 s3, s4, s3
	v_readlane_b32 s4, v240, 37
	s_add_i32 s3, s3, s4
	s_ashr_i32 s4, s3, 31
	s_lshr_b32 s4, s4, 25
	s_add_i32 s4, s3, s4
	s_ashr_i32 s5, s4, 7
	s_lshl_b32 s5, s5, 3
	s_sub_i32 s6, 64, s5
	s_min_i32 s6, s6, 8
	s_abs_i32 s6, s6
	v_cvt_f32_u32_e32 v26, s6
	s_sub_i32 s7, 0, s6
	s_and_b32 s4, s4, 0xffffff80
	s_sub_i32 s3, s3, s4
	v_rcp_iflag_f32_e32 v26, v26
	s_ashr_i32 s4, s3, 31
	s_abs_i32 s3, s3
	v_mov_b32_e32 v44, 0x358637bd
	v_mul_f32_e32 v26, 0x4f7ffffe, v26
	v_cvt_u32_f32_e32 v26, v26
	s_nop 0
	v_readfirstlane_b32 s8, v26
	s_mul_i32 s7, s7, s8
	s_mul_hi_u32 s7, s8, s7
	s_add_i32 s8, s8, s7
	s_mul_hi_u32 s7, s3, s8
	s_mul_i32 s7, s7, s6
	s_sub_i32 s3, s3, s7
	s_sub_i32 s7, s3, s6
	s_cmp_ge_u32 s3, s6
	s_cselect_b32 s3, s7, s3
	s_sub_i32 s7, s3, s6
	s_cmp_ge_u32 s3, s6
	s_cselect_b32 s3, s7, s3
	s_xor_b32 s3, s3, s4
	s_sub_i32 s3, s3, s4
	s_add_i32 s5, s5, s3
	v_lshl_add_u32 v26, s5, 8, v1
	v_ashrrev_i32_e32 v27, 31, v26
	v_lshlrev_b64 v[26:27], 6, v[26:27]
	v_lshl_add_u64 v[38:39], s[92:93], 0, v[26:27]
	global_load_dwordx4 v[26:29], v[38:39], off
	global_load_dwordx4 v[30:33], v[38:39], off offset:16
	global_load_dwordx4 v[34:37], v[38:39], off offset:32
	s_nop 0
	global_load_dwordx4 v[38:41], v[38:39], off offset:48
.Lprs0_p2:
	v_readlane_b32 s4, v240, 45
	v_readlane_b32 s5, v240, 46
	s_andn2_b64 vcc, exec, s[4:5]
	s_cbranch_vccnz .Lprs0_p3
	v_readlane_b32 s4, v240, 48
	v_readlane_b32 s5, v240, 49
	s_and_b64 s[4:5], s[4:5], exec
	v_readlane_b32 s4, v240, 51
	v_readlane_b32 s3, v240, 50
	s_mulk_i32 s4, 0x81
	s_cselect_b32 s3, s4, s3
	v_readlane_b32 s4, v240, 47
	s_add_i32 s3, s3, s4
	s_ashr_i32 s4, s3, 31
	s_lshr_b32 s4, s4, 25
	s_add_i32 s4, s3, s4
	s_ashr_i32 s5, s4, 7
	s_lshl_b32 s5, s5, 3
	s_sub_i32 s6, 64, s5
	s_min_i32 s6, s6, 8
	s_abs_i32 s6, s6
	v_cvt_f32_u32_e32 v50, s6
	s_sub_i32 s7, 0, s6
	s_and_b32 s4, s4, 0xffffff80
	s_sub_i32 s3, s3, s4
	v_rcp_iflag_f32_e32 v50, v50
	s_ashr_i32 s4, s3, 31
	s_abs_i32 s3, s3
	v_mov_b32_e32 v68, 0x358637bd
	v_mul_f32_e32 v50, 0x4f7ffffe, v50
	v_cvt_u32_f32_e32 v50, v50
	s_nop 0
	v_readfirstlane_b32 s8, v50
	s_mul_i32 s7, s7, s8
	s_mul_hi_u32 s7, s8, s7
	s_add_i32 s8, s8, s7
	s_mul_hi_u32 s7, s3, s8
	s_mul_i32 s7, s7, s6
	s_sub_i32 s3, s3, s7
	s_sub_i32 s7, s3, s6
	s_cmp_ge_u32 s3, s6
	s_cselect_b32 s3, s7, s3
	s_sub_i32 s7, s3, s6
	s_cmp_ge_u32 s3, s6
	s_cselect_b32 s3, s7, s3
	s_xor_b32 s3, s3, s4
	s_sub_i32 s3, s3, s4
	s_add_i32 s5, s5, s3
	v_lshl_add_u32 v50, s5, 8, v1
	v_ashrrev_i32_e32 v51, 31, v50
	v_lshlrev_b64 v[50:51], 6, v[50:51]
	v_lshl_add_u64 v[62:63], s[92:93], 0, v[50:51]
	global_load_dwordx4 v[50:53], v[62:63], off
	global_load_dwordx4 v[54:57], v[62:63], off offset:16
	global_load_dwordx4 v[58:61], v[62:63], off offset:32
	s_nop 0
	global_load_dwordx4 v[62:65], v[62:63], off offset:48
.Lprs0_p3:
	v_readlane_b32 s4, v240, 55
	v_readlane_b32 s5, v240, 56
	s_andn2_b64 vcc, exec, s[4:5]
	s_cbranch_vccnz .Lprs0_w
	v_readlane_b32 s4, v240, 60
	v_readlane_b32 s5, v240, 61
	s_and_b64 s[4:5], s[4:5], exec
	v_readlane_b32 s4, v240, 63
	v_readlane_b32 s3, v240, 62
	s_mulk_i32 s4, 0x81
	s_cselect_b32 s3, s4, s3
	v_readlane_b32 s4, v240, 57
	s_add_i32 s3, s3, s4
	s_ashr_i32 s4, s3, 31
	s_lshr_b32 s4, s4, 25
	s_add_i32 s4, s3, s4
	s_ashr_i32 s5, s4, 7
	s_lshl_b32 s5, s5, 3
	s_sub_i32 s6, 64, s5
	s_min_i32 s6, s6, 8
	s_abs_i32 s6, s6
	v_cvt_f32_u32_e32 v74, s6
	s_sub_i32 s7, 0, s6
	s_and_b32 s4, s4, 0xffffff80
	s_sub_i32 s3, s3, s4
	v_rcp_iflag_f32_e32 v74, v74
	s_ashr_i32 s4, s3, 31
	s_abs_i32 s3, s3
	v_mul_f32_e32 v74, 0x4f7ffffe, v74
	v_cvt_u32_f32_e32 v74, v74
	s_nop 0
	v_readfirstlane_b32 s8, v74
	s_mul_i32 s7, s7, s8
	s_mul_hi_u32 s7, s8, s7
	s_add_i32 s8, s8, s7
	s_mul_hi_u32 s7, s3, s8
	s_mul_i32 s7, s7, s6
	s_sub_i32 s3, s3, s7
	s_sub_i32 s7, s3, s6
	s_cmp_ge_u32 s3, s6
	s_cselect_b32 s3, s7, s3
	s_sub_i32 s7, s3, s6
	s_cmp_ge_u32 s3, s6
	s_cselect_b32 s3, s7, s3
	s_xor_b32 s3, s3, s4
	s_sub_i32 s3, s3, s4
	s_add_i32 s5, s5, s3
	v_lshl_add_u32 v74, s5, 8, v1
	v_ashrrev_i32_e32 v75, 31, v74
	v_lshlrev_b64 v[74:75], 6, v[74:75]
	v_lshl_add_u64 v[86:87], s[92:93], 0, v[74:75]
	global_load_dwordx4 v[74:77], v[86:87], off
	global_load_dwordx4 v[78:81], v[86:87], off offset:16
	global_load_dwordx4 v[82:85], v[86:87], off offset:32
	s_nop 0
	global_load_dwordx4 v[86:89], v[86:87], off offset:48
.Lprs0_w:
	s_waitcnt vmcnt(0)
	s_and_b64 vcc, exec, s[52:53]
	s_cbranch_vccnz .Lprs0_c1
	v_mov_b32_e32 v20, 0x358637bd
	s_mov_b32 s3, 0x800000
	s_waitcnt vmcnt(3)
	v_mov_b32_e32 v18, v3
	v_mov_b32_e32 v19, v4
	v_mov_b32_e32 v3, v5
	s_waitcnt vmcnt(2)
	v_mov_b32_e32 v4, v7
	v_mov_b32_e32 v5, v8
	v_mov_b32_e32 v7, v9
	v_pk_add_f32 v[2:3], v[18:19], v[2:3]
	v_pk_add_f32 v[4:5], v[4:5], v[6:7]
	v_pk_add_f32 v[2:3], v[2:3], v[2:3] op_sel:[0,1] op_sel_hi:[1,0]
	v_pk_add_f32 v[4:5], v[4:5], v[4:5] op_sel:[0,1] op_sel_hi:[1,0]
	s_waitcnt vmcnt(1)
	v_add_f32_e32 v8, v10, v11
	v_add_f32_e32 v10, v12, v13
	s_waitcnt vmcnt(0)
	v_mov_b32_e32 v9, v16
	v_mov_b32_e32 v11, v17
	v_mov_b32_e32 v3, v14
	v_mov_b32_e32 v5, v15
	v_pk_add_f32 v[6:7], v[8:9], v[10:11]
	v_pk_add_f32 v[2:3], v[2:3], v[4:5]
	s_nop 0
	v_pk_add_f32 v[2:3], v[2:3], v[6:7]
	s_nop 0
	v_add_f32_e32 v2, v2, v3
	v_fmac_f32_e32 v20, 0x3a800000, v2
	v_mul_f32_e32 v2, 0x4b800000, v20
	v_cmp_gt_f32_e32 vcc, s3, v20
	s_nop 1
	v_cndmask_b32_e32 v2, v20, v2, vcc
	v_rsq_f32_e32 v2, v2
	s_nop 0
	v_mul_f32_e32 v3, 0x45800000, v2
	v_cndmask_b32_e32 v2, v2, v3, vcc
	ds_write_b32 v0, v2
.Lprs0_c1:
	v_readlane_b32 s4, v240, 35
	v_readlane_b32 s5, v240, 36
	s_andn2_b64 vcc, exec, s[4:5]
	s_cbranch_vccnz .Lprs0_c2
	s_mov_b32 s3, 0x800000
	s_waitcnt vmcnt(3)
	v_mov_b32_e32 v42, v27
	v_mov_b32_e32 v43, v28
	v_mov_b32_e32 v27, v29
	s_waitcnt vmcnt(2)
	v_mov_b32_e32 v28, v31
	v_mov_b32_e32 v29, v32
	v_mov_b32_e32 v31, v33
	v_pk_add_f32 v[26:27], v[42:43], v[26:27]
	v_pk_add_f32 v[28:29], v[28:29], v[30:31]
	v_pk_add_f32 v[26:27], v[26:27], v[26:27] op_sel:[0,1] op_sel_hi:[1,0]
	v_pk_add_f32 v[28:29], v[28:29], v[28:29] op_sel:[0,1] op_sel_hi:[1,0]
	s_waitcnt vmcnt(1)
	v_add_f32_e32 v32, v34, v35
	v_add_f32_e32 v34, v36, v37
	s_waitcnt vmcnt(0)
	v_mov_b32_e32 v33, v40
	v_mov_b32_e32 v35, v41
	v_mov_b32_e32 v27, v38
	v_mov_b32_e32 v29, v39
	v_pk_add_f32 v[30:31], v[32:33], v[34:35]
	v_pk_add_f32 v[26:27], v[26:27], v[28:29]
	s_nop 0
	v_pk_add_f32 v[26:27], v[26:27], v[30:31]
	s_nop 0
	v_add_f32_e32 v26, v26, v27
	v_fmac_f32_e32 v44, 0x3a800000, v26
	v_mul_f32_e32 v26, 0x4b800000, v44
	v_cmp_gt_f32_e32 vcc, s3, v44
	s_nop 1
	v_cndmask_b32_e32 v26, v44, v26, vcc
	v_rsq_f32_e32 v26, v26
	s_nop 0
	v_mul_f32_e32 v27, 0x45800000, v26
	v_cndmask_b32_e32 v26, v26, v27, vcc
	ds_write_b32 v0, v26 offset:1024
.Lprs0_c2:
	v_readlane_b32 s4, v240, 45
	v_readlane_b32 s5, v240, 46
	s_andn2_b64 vcc, exec, s[4:5]
	s_cbranch_vccnz .Lprs0_c3
	s_mov_b32 s3, 0x800000
	s_waitcnt vmcnt(3)
	v_mov_b32_e32 v66, v51
	v_mov_b32_e32 v67, v52
	v_mov_b32_e32 v51, v53
	s_waitcnt vmcnt(2)
	v_mov_b32_e32 v52, v55
	v_mov_b32_e32 v53, v56
	v_mov_b32_e32 v55, v57
	v_pk_add_f32 v[50:51], v[66:67], v[50:51]
	v_pk_add_f32 v[52:53], v[52:53], v[54:55]
	v_pk_add_f32 v[50:51], v[50:51], v[50:51] op_sel:[0,1] op_sel_hi:[1,0]
	v_pk_add_f32 v[52:53], v[52:53], v[52:53] op_sel:[0,1] op_sel_hi:[1,0]
	s_waitcnt vmcnt(1)
	v_add_f32_e32 v56, v58, v59
	v_add_f32_e32 v58, v60, v61
	s_waitcnt vmcnt(0)
	v_mov_b32_e32 v57, v64
	v_mov_b32_e32 v59, v65
	v_mov_b32_e32 v51, v62
	v_mov_b32_e32 v53, v63
	v_pk_add_f32 v[54:55], v[56:57], v[58:59]
	v_pk_add_f32 v[50:51], v[50:51], v[52:53]
	s_nop 0
	v_pk_add_f32 v[50:51], v[50:51], v[54:55]
	s_nop 0
	v_add_f32_e32 v50, v50, v51
	v_fmac_f32_e32 v68, 0x3a800000, v50
	v_mul_f32_e32 v50, 0x4b800000, v68
	v_cmp_gt_f32_e32 vcc, s3, v68
	s_nop 1
	v_cndmask_b32_e32 v50, v68, v50, vcc
	v_rsq_f32_e32 v50, v50
	s_nop 0
	v_mul_f32_e32 v51, 0x45800000, v50
	v_cndmask_b32_e32 v50, v50, v51, vcc
	ds_write_b32 v0, v50 offset:2048
.Lprs0_c3:
	v_readlane_b32 s4, v240, 55
	v_readlane_b32 s5, v240, 56
	s_andn2_b64 vcc, exec, s[4:5]
	s_cbranch_vccnz .LBB0_144
	v_mov_b32_e32 v1, 0x358637bd
	s_mov_b32 s3, 0x800000
	s_waitcnt vmcnt(3)
	v_mov_b32_e32 v90, v75
	v_mov_b32_e32 v91, v76
	v_mov_b32_e32 v75, v77
	s_waitcnt vmcnt(2)
	v_mov_b32_e32 v76, v79
	v_mov_b32_e32 v77, v80
	v_mov_b32_e32 v79, v81
	v_pk_add_f32 v[74:75], v[90:91], v[74:75]
	v_pk_add_f32 v[76:77], v[76:77], v[78:79]
	v_pk_add_f32 v[74:75], v[74:75], v[74:75] op_sel:[0,1] op_sel_hi:[1,0]
	v_pk_add_f32 v[76:77], v[76:77], v[76:77] op_sel:[0,1] op_sel_hi:[1,0]
	s_waitcnt vmcnt(1)
	v_add_f32_e32 v80, v82, v83
	v_add_f32_e32 v82, v84, v85
	s_waitcnt vmcnt(0)
	v_mov_b32_e32 v81, v88
	v_mov_b32_e32 v83, v89
	v_mov_b32_e32 v75, v86
	v_mov_b32_e32 v77, v87
	v_pk_add_f32 v[78:79], v[80:81], v[82:83]
	v_pk_add_f32 v[74:75], v[74:75], v[76:77]
	s_nop 0
	v_pk_add_f32 v[74:75], v[74:75], v[78:79]
	s_nop 0
	v_add_f32_e32 v74, v74, v75
	v_fmac_f32_e32 v1, 0x3a800000, v74
	v_mul_f32_e32 v74, 0x4b800000, v1
	v_cmp_gt_f32_e32 vcc, s3, v1
	s_nop 1
	v_cndmask_b32_e32 v1, v1, v74, vcc
	v_rsq_f32_e32 v1, v1
	s_nop 0
	v_mul_f32_e32 v74, 0x45800000, v1
	v_cndmask_b32_e32 v1, v1, v74, vcc
	ds_write_b32 v0, v1 offset:3072

.LBB0_743:
	v_readlane_b32 s3, v242, 8
	s_waitcnt lgkmcnt(0)
	s_barrier
	v_mbcnt_lo_u32_b32 v0, -1, 0
	v_mbcnt_hi_u32_b32 v0, -1, v0
	s_nop 0
	v_add_u32_e32 v1, s3, v0
	s_movk_i32 s3, 0x100
	v_cmp_gt_i32_e32 vcc, s3, v1
	s_and_saveexec_b64 s[6:7], vcc
	s_cbranch_execz .LBB0_752
	s_waitcnt vmcnt(0)
	v_readlane_b32 s4, v241, 5
	s_add_i32 s3, 0, 0x20000
	v_readlane_b32 s5, v241, 6
	s_and_b64 vcc, exec, s[4:5]
	v_lshl_add_u32 v0, v1, 2, s3
	s_cbranch_vccnz .Lprs1_p1
	v_readlane_b32 s4, v240, 29
	v_readlane_b32 s5, v240, 30
	s_and_b64 s[4:5], s[4:5], exec
	v_readlane_b32 s3, v240, 31
	v_readlane_b32 s4, v240, 33
	s_cselect_b32 s3, s4, s3
	s_add_i32 s3, s3, s87
	s_ashr_i32 s4, s3, 31
	s_lshr_b32 s4, s4, 25
	s_add_i32 s4, s3, s4
	s_and_b32 s5, s4, 0xff80
	s_sub_i32 s3, s3, s5
	s_bfe_i32 s5, s3, 0x80000
	s_bfe_u32 s5, s5, 0x3000c
	s_add_i32 s5, s3, s5
	s_and_b32 s5, s5, 0xf8
	s_sub_i32 s3, s3, s5
	s_sext_i32_i8 s3, s3
	s_lshl_b32 s4, s4, 4
	s_and_b32 s4, s4, 0xfffff800
	s_lshl_b32 s3, s3, 8
	s_add_i32 s3, s3, s4
	v_add_u32_e32 v2, s3, v1
	v_ashrrev_i32_e32 v3, 31, v2
	v_lshlrev_b64 v[2:3], 6, v[2:3]
	s_waitcnt vmcnt(1)
	v_lshl_add_u64 v[14:15], s[0:1], 0, v[2:3]
	global_load_dwordx4 v[2:5], v[14:15], off offset:48
	global_load_dwordx4 v[6:9], v[14:15], off offset:32
	global_load_dwordx4 v[10:13], v[14:15], off offset:16
	s_nop 0
	global_load_dwordx4 v[14:17], v[14:15], off
.Lprs1_p1:
	v_readlane_b32 s4, v240, 35
	v_readlane_b32 s5, v240, 36
	s_andn2_b64 vcc, exec, s[4:5]
	s_cbranch_vccnz .Lprs1_p2
	v_readlane_b32 s4, v240, 38
	v_readlane_b32 s5, v240, 39
	s_and_b64 s[4:5], s[4:5], exec
	v_readlane_b32 s4, v240, 41
	v_readlane_b32 s3, v240, 40
	s_mulk_i32 s4, 0x81
	s_cselect_b32 s3, s4, s3
	v_readlane_b32 s4, v240, 37
	s_add_i32 s3, s3, s4
	s_ashr_i32 s4, s3, 31
	s_lshr_b32 s4, s4, 25
	s_add_i32 s4, s3, s4
	s_ashr_i32 s5, s4, 7
	s_and_b32 s4, s4, 0xffffff80
	s_sub_i32 s3, s3, s4
	s_lshl_b32 s4, s5, 3
	s_sub_i32 s5, 64, s4
	s_min_i32 s5, s5, 8
	s_abs_i32 s5, s5
	v_cvt_f32_u32_e32 v26, s5
	s_sub_i32 s9, 0, s5
	s_ashr_i32 s8, s3, 31
	s_abs_i32 s3, s3
	v_rcp_iflag_f32_e32 v26, v26
	s_nop 0
	v_mul_f32_e32 v26, 0x4f7ffffe, v26
	v_cvt_u32_f32_e32 v26, v26
	s_nop 0
	v_readfirstlane_b32 s10, v26
	s_mul_i32 s9, s9, s10
	s_mul_hi_u32 s9, s10, s9
	s_add_i32 s10, s10, s9
	s_mul_hi_u32 s9, s3, s10
	s_mul_i32 s9, s9, s5
	s_sub_i32 s3, s3, s9
	s_sub_i32 s9, s3, s5
	s_cmp_ge_u32 s3, s5
	s_cselect_b32 s3, s9, s3
	s_sub_i32 s9, s3, s5
	s_cmp_ge_u32 s3, s5
	s_cselect_b32 s3, s9, s3
	s_xor_b32 s3, s3, s8
	s_sub_i32 s3, s3, s8
	s_add_i32 s4, s4, s3
	v_lshl_add_u32 v26, s4, 8, v1
	v_ashrrev_i32_e32 v27, 31, v26
	v_lshlrev_b64 v[26:27], 6, v[26:27]
	v_lshl_add_u64 v[38:39], s[0:1], 0, v[26:27]
	global_load_dwordx4 v[26:29], v[38:39], off offset:48
	global_load_dwordx4 v[30:33], v[38:39], off offset:32
	global_load_dwordx4 v[34:37], v[38:39], off offset:16
	s_nop 0
	global_load_dwordx4 v[38:41], v[38:39], off
.Lprs1_p2:
	v_readlane_b32 s4, v240, 45
	v_readlane_b32 s5, v240, 46
	s_andn2_b64 vcc, exec, s[4:5]
	s_cbranch_vccnz .Lprs1_p3
	v_readlane_b32 s4, v240, 48
	v_readlane_b32 s5, v240, 49
	s_and_b64 s[4:5], s[4:5], exec
	v_readlane_b32 s4, v240, 51
	v_readlane_b32 s3, v240, 50
	s_mulk_i32 s4, 0x81
	s_cselect_b32 s3, s4, s3
	v_readlane_b32 s4, v240, 47
	s_add_i32 s3, s3, s4
	s_ashr_i32 s4, s3, 31
	s_lshr_b32 s4, s4, 25
	s_add_i32 s4, s3, s4
	s_ashr_i32 s5, s4, 7
	s_and_b32 s4, s4, 0xffffff80
	s_sub_i32 s3, s3, s4
	s_lshl_b32 s4, s5, 3
	s_sub_i32 s5, 64, s4
	s_min_i32 s5, s5, 8
	s_abs_i32 s5, s5
	v_cvt_f32_u32_e32 v50, s5
	s_sub_i32 s9, 0, s5
	s_ashr_i32 s8, s3, 31
	s_abs_i32 s3, s3
	v_rcp_iflag_f32_e32 v50, v50
	s_nop 0
	v_mul_f32_e32 v50, 0x4f7ffffe, v50
	v_cvt_u32_f32_e32 v50, v50
	s_nop 0
	v_readfirstlane_b32 s10, v50
	s_mul_i32 s9, s9, s10
	s_mul_hi_u32 s9, s10, s9
	s_add_i32 s10, s10, s9
	s_mul_hi_u32 s9, s3, s10
	s_mul_i32 s9, s9, s5
	s_sub_i32 s3, s3, s9
	s_sub_i32 s9, s3, s5
	s_cmp_ge_u32 s3, s5
	s_cselect_b32 s3, s9, s3
	s_sub_i32 s9, s3, s5
	s_cmp_ge_u32 s3, s5
	s_cselect_b32 s3, s9, s3
	s_xor_b32 s3, s3, s8
	s_sub_i32 s3, s3, s8
	s_add_i32 s4, s4, s3
	v_lshl_add_u32 v50, s4, 8, v1
	v_ashrrev_i32_e32 v51, 31, v50
	v_lshlrev_b64 v[50:51], 6, v[50:51]
	v_lshl_add_u64 v[62:63], s[0:1], 0, v[50:51]
	global_load_dwordx4 v[50:53], v[62:63], off offset:48
	global_load_dwordx4 v[54:57], v[62:63], off offset:32
	global_load_dwordx4 v[58:61], v[62:63], off offset:16
	s_nop 0
	global_load_dwordx4 v[62:65], v[62:63], off
.Lprs1_p3:
	v_readlane_b32 s4, v240, 55
	v_readlane_b32 s5, v240, 56
	s_andn2_b64 vcc, exec, s[4:5]
	s_cbranch_vccnz .Lprs1_w
	v_readlane_b32 s4, v240, 60
	v_readlane_b32 s5, v240, 61
	s_and_b64 s[4:5], s[4:5], exec
	v_readlane_b32 s4, v240, 63
	v_readlane_b32 s3, v240, 62
	s_mulk_i32 s4, 0x81
	s_cselect_b32 s3, s4, s3
	v_readlane_b32 s4, v240, 57
	s_add_i32 s3, s3, s4
	s_ashr_i32 s4, s3, 31
	s_lshr_b32 s4, s4, 25
	s_add_i32 s4, s3, s4
	s_ashr_i32 s5, s4, 7
	s_and_b32 s4, s4, 0xffffff80
	s_sub_i32 s3, s3, s4
	s_lshl_b32 s4, s5, 3
	s_sub_i32 s5, 64, s4
	s_min_i32 s5, s5, 8
	s_abs_i32 s5, s5
	v_cvt_f32_u32_e32 v74, s5
	s_sub_i32 s9, 0, s5
	s_ashr_i32 s8, s3, 31
	s_abs_i32 s3, s3
	v_rcp_iflag_f32_e32 v74, v74
	s_nop 0
	v_mul_f32_e32 v74, 0x4f7ffffe, v74
	v_cvt_u32_f32_e32 v74, v74
	s_nop 0
	v_readfirstlane_b32 s10, v74
	s_mul_i32 s9, s9, s10
	s_mul_hi_u32 s9, s10, s9
	s_add_i32 s10, s10, s9
	s_mul_hi_u32 s9, s3, s10
	s_mul_i32 s9, s9, s5
	s_sub_i32 s3, s3, s9
	s_sub_i32 s9, s3, s5
	s_cmp_ge_u32 s3, s5
	s_cselect_b32 s3, s9, s3
	s_sub_i32 s9, s3, s5
	s_cmp_ge_u32 s3, s5
	s_cselect_b32 s3, s9, s3
	s_xor_b32 s3, s3, s8
	s_sub_i32 s3, s3, s8
	s_add_i32 s4, s4, s3
	v_lshl_add_u32 v74, s4, 8, v1
	v_ashrrev_i32_e32 v75, 31, v74
	v_lshlrev_b64 v[74:75], 6, v[74:75]
	v_lshl_add_u64 v[86:87], s[0:1], 0, v[74:75]
	global_load_dwordx4 v[74:77], v[86:87], off offset:48
	global_load_dwordx4 v[78:81], v[86:87], off offset:32
	global_load_dwordx4 v[82:85], v[86:87], off offset:16
	s_nop 0
	global_load_dwordx4 v[86:89], v[86:87], off
.Lprs1_w:
	s_waitcnt vmcnt(0)
	v_readlane_b32 s4, v241, 5
	v_readlane_b32 s5, v241, 6
	s_and_b64 vcc, exec, s[4:5]
	s_cbranch_vccnz .Lprs1_c1
	s_mov_b32 s3, 0x800000
	s_waitcnt vmcnt(2)
	v_add_f32_e32 v6, v6, v7
	v_add_f32_e32 v8, v8, v9
	s_waitcnt vmcnt(0)
	v_mov_b32_e32 v18, v15
	v_mov_b32_e32 v19, v16
	v_mov_b32_e32 v15, v17
	v_mov_b32_e32 v16, v11
	v_mov_b32_e32 v17, v12
	v_mov_b32_e32 v11, v13
	v_pk_add_f32 v[14:15], v[18:19], v[14:15]
	v_pk_add_f32 v[10:11], v[16:17], v[10:11]
	v_pk_add_f32 v[14:15], v[14:15], v[14:15] op_sel:[0,1] op_sel_hi:[1,0]
	v_pk_add_f32 v[10:11], v[10:11], v[10:11] op_sel:[0,1] op_sel_hi:[1,0]
	v_mov_b32_e32 v15, v2
	v_mov_b32_e32 v11, v3
	v_mov_b32_e32 v7, v4
	v_mov_b32_e32 v9, v5
	v_pk_add_f32 v[2:3], v[14:15], v[10:11]
	v_pk_add_f32 v[4:5], v[6:7], v[8:9]
	s_nop 0
	v_pk_add_f32 v[2:3], v[2:3], v[4:5]
	s_nop 0
	v_add_f32_e32 v2, v2, v3
	v_mov_b32_e32 v3, 0x358637bd
	v_fmac_f32_e32 v3, 0x3a800000, v2
	v_cmp_gt_f32_e32 vcc, s3, v3
	v_mul_f32_e32 v2, 0x4b800000, v3
	s_nop 0
	v_cndmask_b32_e32 v2, v3, v2, vcc
	v_rsq_f32_e32 v2, v2
	s_nop 0
	v_mul_f32_e32 v3, 0x45800000, v2
	v_cndmask_b32_e32 v2, v2, v3, vcc
	ds_write_b32 v0, v2
.Lprs1_c1:
	v_readlane_b32 s4, v240, 35
	v_readlane_b32 s5, v240, 36
	s_andn2_b64 vcc, exec, s[4:5]
	s_cbranch_vccnz .Lprs1_c2
	s_mov_b32 s3, 0x800000
	s_waitcnt vmcnt(2)
	v_add_f32_e32 v30, v30, v31
	v_add_f32_e32 v32, v32, v33
	s_waitcnt vmcnt(0)
	v_mov_b32_e32 v42, v39
	v_mov_b32_e32 v43, v40
	v_mov_b32_e32 v39, v41
	v_mov_b32_e32 v40, v35
	v_mov_b32_e32 v41, v36
	v_mov_b32_e32 v35, v37
	v_pk_add_f32 v[38:39], v[42:43], v[38:39]
	v_pk_add_f32 v[34:35], v[40:41], v[34:35]
	v_pk_add_f32 v[38:39], v[38:39], v[38:39] op_sel:[0,1] op_sel_hi:[1,0]
	v_pk_add_f32 v[34:35], v[34:35], v[34:35] op_sel:[0,1] op_sel_hi:[1,0]
	v_mov_b32_e32 v39, v26
	v_mov_b32_e32 v35, v27
	v_mov_b32_e32 v31, v28
	v_mov_b32_e32 v33, v29
	v_pk_add_f32 v[26:27], v[38:39], v[34:35]
	v_pk_add_f32 v[28:29], v[30:31], v[32:33]
	s_nop 0
	v_pk_add_f32 v[26:27], v[26:27], v[28:29]
	s_nop 0
	v_add_f32_e32 v26, v26, v27
	v_mov_b32_e32 v27, 0x358637bd
	v_fmac_f32_e32 v27, 0x3a800000, v26
	v_cmp_gt_f32_e32 vcc, s3, v27
	v_mul_f32_e32 v26, 0x4b800000, v27
	s_nop 0
	v_cndmask_b32_e32 v26, v27, v26, vcc
	v_rsq_f32_e32 v26, v26
	s_nop 0
	v_mul_f32_e32 v27, 0x45800000, v26
	v_cndmask_b32_e32 v26, v26, v27, vcc
	ds_write_b32 v0, v26 offset:1024
.Lprs1_c2:
	v_readlane_b32 s4, v240, 45
	v_readlane_b32 s5, v240, 46
	s_andn2_b64 vcc, exec, s[4:5]
	s_cbranch_vccnz .Lprs1_c3
	s_mov_b32 s3, 0x800000
	s_waitcnt vmcnt(2)
	v_add_f32_e32 v54, v54, v55
	v_add_f32_e32 v56, v56, v57
	s_waitcnt vmcnt(0)
	v_mov_b32_e32 v66, v63
	v_mov_b32_e32 v67, v64
	v_mov_b32_e32 v63, v65
	v_mov_b32_e32 v64, v59
	v_mov_b32_e32 v65, v60
	v_mov_b32_e32 v59, v61
	v_pk_add_f32 v[62:63], v[66:67], v[62:63]
	v_pk_add_f32 v[58:59], v[64:65], v[58:59]
	v_pk_add_f32 v[62:63], v[62:63], v[62:63] op_sel:[0,1] op_sel_hi:[1,0]
	v_pk_add_f32 v[58:59], v[58:59], v[58:59] op_sel:[0,1] op_sel_hi:[1,0]
	v_mov_b32_e32 v63, v50
	v_mov_b32_e32 v59, v51
	v_mov_b32_e32 v55, v52
	v_mov_b32_e32 v57, v53
	v_pk_add_f32 v[50:51], v[62:63], v[58:59]
	v_pk_add_f32 v[52:53], v[54:55], v[56:57]
	s_nop 0
	v_pk_add_f32 v[50:51], v[50:51], v[52:53]
	s_nop 0
	v_add_f32_e32 v50, v50, v51
	v_mov_b32_e32 v51, 0x358637bd
	v_fmac_f32_e32 v51, 0x3a800000, v50
	v_cmp_gt_f32_e32 vcc, s3, v51
	v_mul_f32_e32 v50, 0x4b800000, v51
	s_nop 0
	v_cndmask_b32_e32 v50, v51, v50, vcc
	v_rsq_f32_e32 v50, v50
	s_nop 0
	v_mul_f32_e32 v51, 0x45800000, v50
	v_cndmask_b32_e32 v50, v50, v51, vcc
	ds_write_b32 v0, v50 offset:2048
.Lprs1_c3:
	v_readlane_b32 s4, v240, 55
	v_readlane_b32 s5, v240, 56
	s_andn2_b64 vcc, exec, s[4:5]
	s_cbranch_vccnz .LBB0_752
	s_mov_b32 s0, 0x800000
	s_waitcnt vmcnt(2)
	v_add_f32_e32 v78, v78, v79
	v_add_f32_e32 v80, v80, v81
	s_waitcnt vmcnt(0)
	v_mov_b32_e32 v90, v87
	v_mov_b32_e32 v91, v88
	v_mov_b32_e32 v87, v89
	v_mov_b32_e32 v88, v83
	v_mov_b32_e32 v89, v84
	v_mov_b32_e32 v83, v85
	v_pk_add_f32 v[86:87], v[90:91], v[86:87]
	v_pk_add_f32 v[82:83], v[88:89], v[82:83]
	v_pk_add_f32 v[86:87], v[86:87], v[86:87] op_sel:[0,1] op_sel_hi:[1,0]
	v_pk_add_f32 v[82:83], v[82:83], v[82:83] op_sel:[0,1] op_sel_hi:[1,0]
	v_mov_b32_e32 v87, v74
	v_mov_b32_e32 v83, v75
	v_mov_b32_e32 v79, v76
	v_mov_b32_e32 v81, v77
	v_pk_add_f32 v[74:75], v[86:87], v[82:83]
	v_pk_add_f32 v[76:77], v[78:79], v[80:81]
	s_nop 0
	v_pk_add_f32 v[74:75], v[74:75], v[76:77]
	s_nop 0
	v_add_f32_e32 v1, v74, v75
	v_mov_b32_e32 v74, 0x358637bd
	v_fmac_f32_e32 v74, 0x3a800000, v1
	v_cmp_gt_f32_e32 vcc, s0, v74
	v_mul_f32_e32 v1, 0x4b800000, v74
	s_nop 0
	v_cndmask_b32_e32 v1, v74, v1, vcc
	v_rsq_f32_e32 v1, v1
	s_nop 0
	v_mul_f32_e32 v74, 0x45800000, v1
	v_cndmask_b32_e32 v1, v1, v74, vcc
	ds_write_b32 v0, v1 offset:3072

.LBB0_1303:
	v_readlane_b32 s3, v242, 8
	s_waitcnt lgkmcnt(0)
	s_barrier
	v_mbcnt_lo_u32_b32 v0, -1, 0
	v_mbcnt_hi_u32_b32 v0, -1, v0
	s_nop 0
	v_add_u32_e32 v1, s3, v0
	s_movk_i32 s3, 0x100
	v_cmp_gt_i32_e32 vcc, s3, v1
	s_and_saveexec_b64 s[6:7], vcc
	s_cbranch_execz .LBB0_1312
	s_waitcnt vmcnt(0)
	s_add_i32 s3, 0, 0x20000
	s_and_b64 vcc, exec, s[62:63]
	v_lshl_add_u32 v0, v1, 2, s3
	s_cbranch_vccnz .Lprs2_p1
	v_readlane_b32 s4, v240, 29
	v_readlane_b32 s5, v240, 30
	s_and_b64 s[4:5], s[4:5], exec
	v_readlane_b32 s3, v240, 31
	v_readlane_b32 s4, v240, 33
	s_cselect_b32 s3, s4, s3
	s_add_i32 s3, s3, s87
	s_ashr_i32 s4, s3, 31
	s_lshr_b32 s4, s4, 25
	s_add_i32 s4, s3, s4
	s_and_b32 s5, s4, 0xff80
	s_sub_i32 s3, s3, s5
	s_bfe_i32 s5, s3, 0x80000
	s_bfe_u32 s5, s5, 0x3000c
	s_add_i32 s5, s3, s5
	s_and_b32 s5, s5, 0xf8
	s_sub_i32 s3, s3, s5
	s_sext_i32_i8 s3, s3
	s_lshl_b32 s4, s4, 4
	s_and_b32 s4, s4, 0xfffff800
	s_lshl_b32 s3, s3, 8
	s_add_i32 s3, s3, s4
	v_add_u32_e32 v2, s3, v1
	v_ashrrev_i32_e32 v3, 31, v2
	v_lshlrev_b64 v[2:3], 6, v[2:3]
	v_lshl_add_u64 v[14:15], s[0:1], 0, v[2:3]
	global_load_dwordx4 v[2:5], v[14:15], off offset:48
	global_load_dwordx4 v[6:9], v[14:15], off offset:32
	global_load_dwordx4 v[10:13], v[14:15], off offset:16
	s_nop 0
	global_load_dwordx4 v[14:17], v[14:15], off
.Lprs2_p1:
	v_readlane_b32 s4, v240, 35
	v_readlane_b32 s5, v240, 36
	s_andn2_b64 vcc, exec, s[4:5]
	s_cbranch_vccnz .Lprs2_p2
	v_readlane_b32 s4, v240, 38
	v_readlane_b32 s5, v240, 39
	s_and_b64 s[4:5], s[4:5], exec
	v_readlane_b32 s3, v240, 40
	v_readlane_b32 s4, v240, 42
	s_cselect_b32 s3, s4, s3
	v_readlane_b32 s4, v240, 37
	s_add_i32 s3, s3, s4
	s_ashr_i32 s4, s3, 31
	s_lshr_b32 s4, s4, 25
	s_add_i32 s4, s3, s4
	s_ashr_i32 s5, s4, 7
	s_and_b32 s4, s4, 0xffffff80
	s_sub_i32 s3, s3, s4
	s_lshl_b32 s4, s5, 3
	s_sub_i32 s5, 64, s4
	s_min_i32 s5, s5, 8
	s_abs_i32 s5, s5
	v_cvt_f32_u32_e32 v26, s5
	s_sub_i32 s9, 0, s5
	s_ashr_i32 s8, s3, 31
	s_abs_i32 s3, s3
	v_rcp_iflag_f32_e32 v26, v26
	s_nop 0
	v_mul_f32_e32 v26, 0x4f7ffffe, v26
	v_cvt_u32_f32_e32 v26, v26
	s_nop 0
	v_readfirstlane_b32 s10, v26
	s_mul_i32 s9, s9, s10
	s_mul_hi_u32 s9, s10, s9
	s_add_i32 s10, s10, s9
	s_mul_hi_u32 s9, s3, s10
	s_mul_i32 s9, s9, s5
	s_sub_i32 s3, s3, s9
	s_sub_i32 s9, s3, s5
	s_cmp_ge_u32 s3, s5
	s_cselect_b32 s3, s9, s3
	s_sub_i32 s9, s3, s5
	s_cmp_ge_u32 s3, s5
	s_cselect_b32 s3, s9, s3
	s_xor_b32 s3, s3, s8
	s_sub_i32 s3, s3, s8
	s_add_i32 s4, s4, s3
	v_lshl_add_u32 v26, s4, 8, v1
	v_ashrrev_i32_e32 v27, 31, v26
	v_lshlrev_b64 v[26:27], 6, v[26:27]
	v_lshl_add_u64 v[38:39], s[0:1], 0, v[26:27]
	global_load_dwordx4 v[26:29], v[38:39], off offset:48
	global_load_dwordx4 v[30:33], v[38:39], off offset:32
	global_load_dwordx4 v[34:37], v[38:39], off offset:16
	s_nop 0
	global_load_dwordx4 v[38:41], v[38:39], off
.Lprs2_p2:
	v_readlane_b32 s4, v240, 45
	v_readlane_b32 s5, v240, 46
	s_andn2_b64 vcc, exec, s[4:5]
	s_cbranch_vccnz .Lprs2_p3
	v_readlane_b32 s4, v240, 48
	v_readlane_b32 s5, v240, 49
	s_and_b64 s[4:5], s[4:5], exec
	v_readlane_b32 s3, v240, 50
	v_readlane_b32 s4, v240, 52
	s_cselect_b32 s3, s4, s3
	v_readlane_b32 s4, v240, 47
	s_add_i32 s3, s3, s4
	s_ashr_i32 s4, s3, 31
	s_lshr_b32 s4, s4, 25
	s_add_i32 s4, s3, s4
	s_ashr_i32 s5, s4, 7
	s_and_b32 s4, s4, 0xffffff80
	s_sub_i32 s3, s3, s4
	s_lshl_b32 s4, s5, 3
	s_sub_i32 s5, 64, s4
	s_min_i32 s5, s5, 8
	s_abs_i32 s5, s5
	v_cvt_f32_u32_e32 v50, s5
	s_sub_i32 s9, 0, s5
	s_ashr_i32 s8, s3, 31
	s_abs_i32 s3, s3
	v_rcp_iflag_f32_e32 v50, v50
	s_nop 0
	v_mul_f32_e32 v50, 0x4f7ffffe, v50
	v_cvt_u32_f32_e32 v50, v50
	s_nop 0
	v_readfirstlane_b32 s10, v50
	s_mul_i32 s9, s9, s10
	s_mul_hi_u32 s9, s10, s9
	s_add_i32 s10, s10, s9
	s_mul_hi_u32 s9, s3, s10
	s_mul_i32 s9, s9, s5
	s_sub_i32 s3, s3, s9
	s_sub_i32 s9, s3, s5
	s_cmp_ge_u32 s3, s5
	s_cselect_b32 s3, s9, s3
	s_sub_i32 s9, s3, s5
	s_cmp_ge_u32 s3, s5
	s_cselect_b32 s3, s9, s3
	s_xor_b32 s3, s3, s8
	s_sub_i32 s3, s3, s8
	s_add_i32 s4, s4, s3
	v_lshl_add_u32 v50, s4, 8, v1
	v_ashrrev_i32_e32 v51, 31, v50
	v_lshlrev_b64 v[50:51], 6, v[50:51]
	v_lshl_add_u64 v[62:63], s[0:1], 0, v[50:51]
	global_load_dwordx4 v[50:53], v[62:63], off offset:48
	global_load_dwordx4 v[54:57], v[62:63], off offset:32
	global_load_dwordx4 v[58:61], v[62:63], off offset:16
	s_nop 0
	global_load_dwordx4 v[62:65], v[62:63], off
.Lprs2_p3:
	v_readlane_b32 s4, v240, 55
	v_readlane_b32 s5, v240, 56
	s_andn2_b64 vcc, exec, s[4:5]
	s_cbranch_vccnz .Lprs2_w
	v_readlane_b32 s4, v240, 60
	v_readlane_b32 s5, v240, 61
	s_and_b64 s[4:5], s[4:5], exec
	v_readlane_b32 s3, v240, 62
	v_readlane_b32 s4, v241, 0
	s_cselect_b32 s3, s4, s3
	v_readlane_b32 s4, v240, 57
	s_add_i32 s3, s3, s4
	s_ashr_i32 s4, s3, 31
	s_lshr_b32 s4, s4, 25
	s_add_i32 s4, s3, s4
	s_ashr_i32 s5, s4, 7
	s_and_b32 s4, s4, 0xffffff80
	s_sub_i32 s3, s3, s4
	s_lshl_b32 s4, s5, 3
	s_sub_i32 s5, 64, s4
	s_min_i32 s5, s5, 8
	s_abs_i32 s5, s5
	v_cvt_f32_u32_e32 v74, s5
	s_sub_i32 s9, 0, s5
	s_ashr_i32 s8, s3, 31
	s_abs_i32 s3, s3
	v_rcp_iflag_f32_e32 v74, v74
	s_nop 0
	v_mul_f32_e32 v74, 0x4f7ffffe, v74
	v_cvt_u32_f32_e32 v74, v74
	s_nop 0
	v_readfirstlane_b32 s10, v74
	s_mul_i32 s9, s9, s10
	s_mul_hi_u32 s9, s10, s9
	s_add_i32 s10, s10, s9
	s_mul_hi_u32 s9, s3, s10
	s_mul_i32 s9, s9, s5
	s_sub_i32 s3, s3, s9
	s_sub_i32 s9, s3, s5
	s_cmp_ge_u32 s3, s5
	s_cselect_b32 s3, s9, s3
	s_sub_i32 s9, s3, s5
	s_cmp_ge_u32 s3, s5
	s_cselect_b32 s3, s9, s3
	s_xor_b32 s3, s3, s8
	s_sub_i32 s3, s3, s8
	s_add_i32 s4, s4, s3
	v_lshl_add_u32 v74, s4, 8, v1
	v_ashrrev_i32_e32 v75, 31, v74
	v_lshlrev_b64 v[74:75], 6, v[74:75]
	v_lshl_add_u64 v[86:87], s[0:1], 0, v[74:75]
	global_load_dwordx4 v[74:77], v[86:87], off offset:48
	global_load_dwordx4 v[78:81], v[86:87], off offset:32
	global_load_dwordx4 v[82:85], v[86:87], off offset:16
	s_nop 0
	global_load_dwordx4 v[86:89], v[86:87], off
.Lprs2_w:
	s_waitcnt vmcnt(0)
	s_and_b64 vcc, exec, s[62:63]
	s_cbranch_vccnz .Lprs2_c1
	s_mov_b32 s3, 0x800000
	s_waitcnt vmcnt(2)
	v_add_f32_e32 v6, v6, v7
	v_add_f32_e32 v8, v8, v9
	s_waitcnt vmcnt(0)
	v_mov_b32_e32 v18, v15
	v_mov_b32_e32 v19, v16
	v_mov_b32_e32 v15, v17
	v_mov_b32_e32 v16, v11
	v_mov_b32_e32 v17, v12
	v_mov_b32_e32 v11, v13
	v_pk_add_f32 v[14:15], v[18:19], v[14:15]
	v_pk_add_f32 v[10:11], v[16:17], v[10:11]
	v_pk_add_f32 v[14:15], v[14:15], v[14:15] op_sel:[0,1] op_sel_hi:[1,0]
	v_pk_add_f32 v[10:11], v[10:11], v[10:11] op_sel:[0,1] op_sel_hi:[1,0]
	v_mov_b32_e32 v15, v2
	v_mov_b32_e32 v11, v3
	v_mov_b32_e32 v7, v4
	v_mov_b32_e32 v9, v5
	v_pk_add_f32 v[2:3], v[14:15], v[10:11]
	v_pk_add_f32 v[4:5], v[6:7], v[8:9]
	s_nop 0
	v_pk_add_f32 v[2:3], v[2:3], v[4:5]
	s_nop 0
	v_add_f32_e32 v2, v2, v3
	v_mov_b32_e32 v3, 0x358637bd
	v_fmac_f32_e32 v3, 0x3a800000, v2
	v_cmp_gt_f32_e32 vcc, s3, v3
	v_mul_f32_e32 v2, 0x4b800000, v3
	s_nop 0
	v_cndmask_b32_e32 v2, v3, v2, vcc
	v_rsq_f32_e32 v2, v2
	s_nop 0
	v_mul_f32_e32 v3, 0x45800000, v2
	v_cndmask_b32_e32 v2, v2, v3, vcc
	ds_write_b32 v0, v2
